# attention waves no longer raise their priority over the co-resident decode waves
# speedup vs baseline: 1.0195x; 1.0114x over previous
; template <int MASK> __device__ __forceinline__ void phase3(const Params& p, LAS unsigned char* lds, volatile LAS unsigned* ctlw, int qset) {
;     ...
;     const unsigned gb0 = __builtin_amdgcn_readfirstlane(ctlw[20]);
;     __syncthreads();
;     {
;         int tid = threadIdx.x; asm volatile("" : "+v"(tid));
;         const int wid = __builtin_amdgcn_readfirstlane(tid >> 6), lane = tid & 63;
;         if (wid < 4) {
;             GroupBar gb; gb.cnt = ctlw + 20; gb.gen = gb0;
;             __builtin_amdgcn_s_setprio(1);
.LBB0_835:
	s_add_i32 s53, 0, 0x27e50
	v_mov_b32_e32 v1, s53
	ds_read_b32 v1, v1
	v_mov_b32_e32 v193, v0
	s_waitcnt lgkmcnt(0)
	s_barrier
	s_mov_b32 s45, 0
	v_readfirstlane_b32 s2, v193
	s_ashr_i32 s24, s2, 6
	v_and_b32_e32 v169, 63, v193
	v_readfirstlane_b32 s54, v1
	s_cmp_gt_i32 s24, 3
	v_cmp_eq_u32_e64 s[2:3], 0, v169
	s_cbranch_scc1 .LBB0_961
	s_add_u32 s33, s90, 0xe000000
	s_addc_u32 s52, s91, 0
	s_setprio 0
	v_mov_b32_e32 v3, 0
	v_mov_b32_e32 v194, s53
	s_movk_i32 s55, 0x3600
	s_movk_i32 s62, 0x70
	s_mov_b32 s63, 0xfffff0
	s_movk_i32 s64, 0xc0
	s_movk_i32 s65, 0x60
	s_movk_i32 s66, 0x80
	s_movk_i32 s67, 0xa0
	s_movk_i32 s70, 0xe0
	s_movk_i32 s71, 0x118
	s_mov_b32 s72, 0
	s_branch .LBB0_839
